# type-B workgroups run their attention units first and their conv tile afterwards (conv arrival right after it), so conv and attention phases of the two workgroup types overlap
# speedup vs baseline: 1.0019x; 1.0019x over previous
.LBB0_341:
	s_cmp_lt_i32 s26, 4
	s_cselect_b64 s[6:7], -1, 0
	s_and_b64 s[30:31], s[6:7], s[4:5]
	s_andn2_b64 vcc, exec, s[30:31]
	s_cbranch_vccnz .LBB0_509
	v_and_b32_e32 v2, 63, v0
	s_cmpk_gt_i32 s2, 0xff
	s_mov_b64 s[34:35], s[24:25]
	s_mov_b32 s32, 0
	v_mov_b32_e32 v254, v2
	s_cbranch_scc1 .LBB0_383
	s_bitcmp1_b32 s2, 5
	s_cbranch_scc0 .Lconv_entry
	s_mov_b32 s11, 0
	s_mov_b64 s[4:5], exec
	s_branch .LBB0_385
.Lconv_entry:
	s_and_b32 s5, s29, 0x3fffffc0
	v_lshlrev_b32_e32 v1, 4, v0
	v_lshlrev_b32_e32 v4, 2, v0
	s_add_i32 s4, 0, 0x1f000
	s_lshl_b32 s5, s5, 2
	v_and_b32_e32 v6, 0x7f0, v1
	v_mov_b32_e32 v7, 0
	v_add_u32_e32 v206, s4, v4
	v_lshlrev_b32_e32 v66, 3, v0
	s_add_i32 s16, s4, s5
	v_lshl_add_u64 v[8:9], s[34:35], 0, v[6:7]
	s_mov_b64 s[4:5], 0x9000000
	v_mov_b32_e32 v67, v7
	v_lshl_add_u64 v[68:69], v[8:9], 0, s[4:5]
	v_lshl_add_u64 v[8:9], s[34:35], 0, v[66:67]
	s_mov_b64 s[22:23], 0x2b0f600
	v_lshl_add_u64 v[80:81], v[8:9], 0, s[22:23]
	s_mov_b64 s[22:23], 0x2b10600
	v_lshl_add_u64 v[82:83], v[8:9], 0, s[22:23]
	s_mov_b64 s[22:23], 0x2b11600
	v_lshl_add_u64 v[84:85], v[8:9], 0, s[22:23]
	s_mov_b64 s[22:23], 0x2b12600
	v_lshl_add_u64 v[86:87], v[8:9], 0, s[22:23]
	s_mov_b64 s[22:23], 0x2b13600
	v_lshl_add_u64 v[88:89], v[8:9], 0, s[22:23]
	s_mov_b64 s[22:23], 0x2b14600
	v_lshl_add_u64 v[90:91], v[8:9], 0, s[22:23]
	s_mov_b64 s[22:23], 0x2b15600
	v_lshl_add_u64 v[92:93], v[8:9], 0, s[22:23]
	s_mov_b64 s[22:23], 0x2b16600
	v_lshl_add_u64 v[94:95], v[8:9], 0, s[22:23]
	s_mov_b64 s[22:23], 0x2b17600
	v_lshl_add_u64 v[96:97], v[8:9], 0, s[22:23]
	s_mov_b64 s[22:23], 0x2b18600
	v_lshl_add_u64 v[98:99], v[8:9], 0, s[22:23]
	s_mov_b64 s[22:23], 0x2b19600
	v_lshl_add_u64 v[100:101], v[8:9], 0, s[22:23]
	s_mov_b64 s[22:23], 0x2b1a600
	s_mov_b64 s[4:5], 0x2b0e600
	v_lshl_add_u64 v[102:103], v[8:9], 0, s[22:23]
	s_mov_b64 s[22:23], 0x2b1b600
	v_lshl_add_u64 v[70:71], v[8:9], 0, s[4:5]
	s_mov_b64 s[4:5], 0x2b00600
	v_and_b32_e32 v3, 32, v2
	v_lshl_add_u64 v[104:105], v[8:9], 0, s[22:23]
	s_mov_b64 s[22:23], 0x2b1c600
	v_lshl_add_u64 v[72:73], v[8:9], 0, s[4:5]
	v_cmp_eq_u32_e64 s[4:5], 0, v3
	v_and_b32_e32 v3, 16, v2
	v_lshl_add_u64 v[106:107], v[8:9], 0, s[22:23]
	s_mov_b64 s[22:23], 0x2b1d600
	v_cmp_eq_u32_e64 s[6:7], 0, v3
	v_and_b32_e32 v3, 8, v2
	v_lshl_add_u64 v[108:109], v[8:9], 0, s[22:23]
	s_mov_b64 s[22:23], 0x2b1e600
	v_cmp_eq_u32_e64 s[8:9], 0, v3
	v_and_b32_e32 v3, 4, v2
	v_lshl_add_u64 v[110:111], v[8:9], 0, s[22:23]
	s_mov_b64 s[22:23], 0x2b1f600
	v_cmp_eq_u32_e64 s[10:11], 0, v3
	v_and_b32_e32 v3, 2, v2
	v_lshl_add_u32 v67, v2, 2, s16
	s_mov_b64 s[16:17], 0x2b01600
	v_lshl_add_u64 v[112:113], v[8:9], 0, s[22:23]
	s_mov_b64 s[22:23], 0x2b20600
	v_cmp_eq_u32_e64 s[12:13], 0, v3
	v_and_b32_e32 v3, 1, v2
	v_lshl_add_u64 v[74:75], v[8:9], 0, s[16:17]
	s_mov_b64 s[16:17], 0x2b02600
	v_mov_b32_e32 v5, v7
	v_lshl_add_u64 v[114:115], v[8:9], 0, s[22:23]
	s_mov_b64 s[22:23], 0x2b21600
	v_cmp_eq_u32_e64 s[14:15], 0, v3
	v_lshl_add_u64 v[76:77], v[8:9], 0, s[16:17]
	v_lshl_add_u64 v[2:3], s[34:35], 0, v[4:5]
	s_mov_b64 s[16:17], 0xd000000
	v_lshl_add_u64 v[116:117], v[8:9], 0, s[22:23]
	s_mov_b64 s[22:23], 0x2b22600
	v_lshl_add_u64 v[78:79], v[2:3], 0, s[16:17]
	v_or_b32_e32 v2, 0x200, v0
	v_lshl_add_u64 v[118:119], v[8:9], 0, s[22:23]
	s_mov_b64 s[22:23], 0x2b23600
	v_lshrrev_b32_e32 v208, 7, v2
	v_or_b32_e32 v2, 0x600, v0
	v_lshl_add_u64 v[120:121], v[8:9], 0, s[22:23]
	s_mov_b64 s[22:23], 0x2b24600
	v_lshrrev_b32_e32 v210, 7, v2
	v_or_b32_e32 v2, 0xa00, v0
	v_lshl_add_u64 v[122:123], v[8:9], 0, s[22:23]
	s_mov_b64 s[22:23], 0x2b25600
	v_lshrrev_b32_e32 v213, 7, v2
	v_or_b32_e32 v2, 0xe00, v0
	v_lshl_add_u64 v[124:125], v[8:9], 0, s[22:23]
	s_mov_b64 s[22:23], 0x2b26600
	v_lshrrev_b32_e32 v214, 7, v2
	v_or_b32_e32 v2, 0x1000, v0
	v_lshl_add_u64 v[126:127], v[8:9], 0, s[22:23]
	s_mov_b64 s[22:23], 0x2b27600
	v_lshrrev_b32_e32 v215, 7, v2
	v_lshl_add_u64 v[128:129], v[8:9], 0, s[22:23]
	s_mov_b64 s[22:23], 0x2b28600
	v_lshl_add_u32 v224, v2, 4, 0
	v_or_b32_e32 v2, 0xc00, v0
	v_lshl_add_u64 v[130:131], v[8:9], 0, s[22:23]
	s_mov_b64 s[22:23], 0x2b29600
	v_lshrrev_b32_e32 v2, 7, v2
	v_or_b32_e32 v3, 0x1200, v0
	v_lshl_add_u64 v[132:133], v[8:9], 0, s[22:23]
	s_mov_b64 s[22:23], 0x2b2a600
	v_subrev_u32_e32 v241, 30, v2
	v_or_b32_e32 v2, 0x800, v0
	v_add_u32_e32 v202, 0, v4
	v_lshrrev_b32_e32 v216, 7, v3
	v_or_b32_e32 v3, 0x1400, v0
	v_or_b32_e32 v4, 0x1600, v0
	v_or_b32_e32 v5, 0x1a00, v0
	v_lshl_add_u64 v[134:135], v[8:9], 0, s[22:23]
	s_mov_b64 s[22:23], 0x2b2b600
	v_lshrrev_b32_e32 v2, 7, v2
	v_lshrrev_b32_e32 v207, 7, v0
	v_lshrrev_b32_e32 v209, 7, v194
	v_lshrrev_b32_e32 v217, 7, v3
	v_lshrrev_b32_e32 v218, 7, v4
	v_or_b32_e32 v4, 0x1800, v0
	v_lshrrev_b32_e32 v220, 7, v5
	v_or_b32_e32 v5, 0x1c00, v0
	s_movk_i32 s16, 0x1f00
	v_or_b32_e32 v6, 0x1e00, v0
	s_movk_i32 s18, 0x100
	v_lshl_add_u64 v[136:137], v[8:9], 0, s[22:23]
	s_mov_b64 s[22:23], 0x2b2c600
	v_add_u32_e32 v223, 0, v1
	v_subrev_u32_e32 v243, 30, v2
	v_mbcnt_lo_u32_b32 v2, -1, 0
	v_add_u32_e32 v203, 0x1d800, v202
	v_add_u32_e32 v204, 0x1e000, v202
	v_add_u32_e32 v205, 0x1e800, v202
	v_cmp_gt_u32_e64 s[20:21], 32, v0
	v_lshrrev_b32_e32 v212, 7, v195
	v_lshrrev_b32_e32 v211, 7, v211
	v_lshrrev_b32_e32 v219, 7, v4
	v_lshrrev_b32_e32 v221, 7, v5
	v_cmp_gt_u32_e64 s[16:17], s16, v5
	v_lshrrev_b32_e32 v222, 7, v6
	v_cmp_gt_u32_e64 s[18:19], s18, v0
	v_lshl_add_u64 v[138:139], v[8:9], 0, s[22:23]
	v_add_u32_e32 v225, 0x12000, v223
	v_lshl_add_u32 v226, v3, 4, 0
	v_add_u32_e32 v227, 0x16000, v223
	v_lshl_add_u32 v228, v4, 4, 0
	v_add_u32_e32 v229, 0x1a000, v223
	v_lshl_add_u32 v230, v5, 4, 0
	s_lshl_b32 s36, s2, 5
	s_lshl_b32 s39, s3, 5
	v_subrev_u32_e32 v1, 30, v218
	v_subrev_u32_e32 v231, 30, v217
	v_subrev_u32_e32 v238, 30, v216
	v_subrev_u32_e32 v239, 30, v215
	v_subrev_u32_e32 v240, 30, v214
	v_subrev_u32_e32 v242, 30, v213
	v_subrev_u32_e32 v244, 30, v210
	v_subrev_u32_e32 v245, 30, v209
	v_subrev_u32_e32 v246, 30, v208
	v_subrev_u32_e32 v247, 30, v207
	s_mov_b32 s38, 0x3a800000
	s_mov_b32 s42, 0xf800000
	v_mov_b32_e32 v248, 0x260
	s_add_i32 s43, 0, 0x1f800
	s_add_i32 s44, 0, 0x1f808
	s_add_i32 s45, 0, 0x1f810
	s_add_i32 s46, 0, 0x1f818
	s_add_i32 s47, 0, 0x1f820
	s_add_i32 s48, 0, 0x1f828
	s_add_i32 s49, 0, 0x1f830
	s_add_i32 s50, 0, 0x1f838
	s_add_i32 s51, 0, 0x1f840
	s_add_i32 s52, 0, 0x1f848
	s_add_i32 s53, 0, 0x1f850
	s_add_i32 s54, 0, 0x1f858
	s_add_i32 s55, 0, 0x1f860
	s_add_i32 s56, 0, 0x1f868
	s_add_i32 s57, 0, 0x1f870
	s_add_i32 s58, 0, 0x1f878
	s_add_i32 s59, 0, 0x1f880
	s_add_i32 s60, 0, 0x1f888
	s_add_i32 s61, 0, 0x1f890
	s_add_i32 s62, 0, 0x1f898
	s_add_i32 s63, 0, 0x1f8a0
	s_add_i32 s64, 0, 0x1f8a8
	s_add_i32 s65, 0, 0x1f8b0
	s_add_i32 s66, 0, 0x1f8b8
	s_add_i32 s67, 0, 0x1f8c0
	s_add_i32 s68, 0, 0x1f8c8
	s_add_i32 s69, 0, 0x1f8d0
	s_add_i32 s73, 0, 0x1f8d8
	s_add_i32 s74, 0, 0x1f8e0
	s_add_i32 s75, 0, 0x1f8e8
	s_add_i32 s76, 0, 0x1f8f0
	s_add_i32 s77, 0, 0x1f8f8
	v_mbcnt_hi_u32_b32 v249, -1, v2
	s_mov_b32 s78, s2
	s_branch .LBB0_345

.LBB0_385:
	s_or_b64 exec, exec, s[4:5]
	s_cmp_lg_u32 s32, 1
	s_cbranch_scc1 .Lst_norm
.Lt2_entry:
	s_mov_b32 s32, 2
	s_mov_b64 s[98:99], exec
	v_cmp_eq_u32_e64 s[100:101], 0, v0
	s_and_b64 exec, exec, s[100:101]
	s_cbranch_execz .Lst_rest
	s_waitcnt vmcnt(0)
	v_mov_b32_e32 v250, 0x6000
	v_mov_b32_e32 v251, 1
	global_atomic_add v250, v251, s[24:25]
.Lst_rest:
	s_mov_b64 exec, s[98:99]
	s_and_b32 s66, s2, 7
	s_lshr_b32 s67, s2, 3
	s_mov_b64 s[8:9], -1
	v_and_b32_e32 v254, 63, v0
	s_branch .LBB0_476
.Lst_norm:
	s_ashr_i32 s6, s2, 31
	s_lshr_b32 s6, s6, 29
	s_add_i32 s6, s2, s6
	s_and_b32 s7, s6, -8
	s_ashr_i32 s5, s3, 3
	s_sub_i32 s66, s2, s7
	s_mul_i32 s5, s5, s66
	s_ashr_i32 s67, s6, 3
	s_and_b32 s4, s3, 7
	s_add_i32 s5, s5, s67
	s_cmpk_eq_i32 s3, 0x100
	s_cselect_b64 s[8:9], -1, 0
	s_cmpk_lg_i32 s3, 0x100
	s_mov_b64 s[14:15], s[24:25]
	s_cselect_b64 s[12:13], -1, 0
	s_add_u32 s68, s14, 0x5000000
	s_addc_u32 s69, s15, 0
	s_add_u32 s73, s14, 0x6000000
	s_addc_u32 s74, s15, 0
	s_add_u32 s75, s14, 0x7000000
	s_addc_u32 s76, s15, 0
	s_cmp_eq_u32 s4, 0
	s_cselect_b32 s77, s5, s2
	s_and_b32 s5, s77, 3
	s_and_b32 s6, s77, 2
	s_add_i32 s6, s6, s5
	s_and_b32 s4, s77, 4
	s_ashr_i32 s78, s77, 3
	s_sub_i32 s7, 13, s6
	s_xor_b32 s10, s5, 15
	s_sub_i32 s16, 13, s5
	s_add_i32 s17, s5, 2
	s_or_b32 s18, s5, 4
	s_cmp_lt_u32 s5, 2
	s_cselect_b32 s5, s10, s16
	s_cselect_b32 s10, s17, s18
	s_cmp_eq_u32 s4, 0
	s_cselect_b32 s79, s5, s7
	s_cselect_b32 s80, s10, s6
	v_mov_b32_e32 v223, 0
	s_mov_b64 s[16:17], 0x80
	s_mov_b64 s[18:19], 0x20000
	s_mov_b64 s[20:21], 0x40000
	s_mov_b64 s[22:23], 0x60000
	s_mov_b64 s[34:35], 0x20080
	s_mov_b64 s[36:37], 0x6080000
	s_mov_b64 s[38:39], 0x7040000
	s_mov_b64 s[40:41], 0x7040080
	s_mov_b32 s81, 0x41000000
	s_mov_b64 s[42:43], 0x60a0000
	s_mov_b64 s[44:45], 0x7060000
	s_mov_b64 s[46:47], 0x7060080
	s_mov_b64 s[48:49], 0x6060000
	s_mov_b64 s[50:51], 0x7020000
	s_mov_b64 s[52:53], 0x7020080
	s_mov_b32 s82, 0xb000000
	v_mov_b32_e32 v232, 0xff800000
	s_mov_b32 s83, 0
	v_mov_b32_e32 v178, v254
	s_branch .LBB0_388

.LBB0_396:
	s_bitcmp1_b32 s2, 5
	s_cbranch_scc1 .Lcv_skip
	s_cmp_lg_u32 s83, 1
	s_cbranch_scc1 .Lcv_skip
	s_mov_b64 s[98:99], exec
	v_cmp_eq_u32_e64 s[100:101], 0, v0
	s_and_b64 exec, exec, s[100:101]
	s_cbranch_execz .Lcv_rest
	v_mov_b32_e32 v250, 0x6000
	v_mov_b32_e32 v251, 1
	global_atomic_add v250, v251, s[24:25]

.LBB0_476:
	s_ashr_i32 s4, s3, 31
	s_lshr_b32 s4, s4, 29
	s_add_i32 s4, s3, s4
	v_lshlrev_b32_e32 v1, 6, v0
	s_ashr_i32 s4, s4, 3
	v_and_b32_e32 v149, 0x3c0, v1
	v_lshlrev_b32_e32 v1, 2, v0
	s_mul_i32 s20, s4, s66
	v_and_b32_e32 v147, 32, v1
	v_lshrrev_b32_e32 v1, 5, v0
	v_lshrrev_b32_e32 v3, 1, v0
	s_add_i32 s20, s20, s67
	v_and_b32_e32 v1, 4, v1
	v_bfe_u32 v2, v0, 2, 2
	v_and_b32_e32 v142, 24, v3
	s_and_b32 s22, s20, 3
	v_or3_b32 v1, v1, v2, v142
	v_lshlrev_b32_e32 v2, 4, v0
	s_bitcmp0_b32 s20, 2
	v_or_b32_e32 v145, 0x2000, v2
	s_cselect_b64 s[4:5], -1, 0
	v_lshrrev_b32_e32 v3, 7, v145
	s_movk_i32 s6, 0x60
	v_and_b32_e32 v4, 32, v0
	s_and_b64 s[4:5], s[8:9], s[4:5]
	v_and_or_b32 v150, v3, s6, v1
	v_bitop3_b32 v143, v2, v4, 48 bitop3:0x6c
	v_and_b32_e32 v144, 64, v0
	v_bfe_u32 v146, v0, 2, 4
	s_movk_i32 s6, 0x70
	v_lshrrev_b32_e32 v2, 3, v0
	v_and_b32_e32 v148, 15, v0
	v_or_b32_e32 v151, v143, v144
	v_and_or_b32 v152, v3, s6, v146
	v_and_or_b32 v153, v2, 32, v1
	v_and_or_b32 v154, v2, 48, v146
	s_mov_b64 s[6:7], s[24:25]
	s_andn2_b64 vcc, exec, s[4:5]
	s_mov_b64 s[4:5], -1
	s_cbranch_vccz .LBB0_494
	s_andn2_b64 vcc, exec, s[8:9]
	s_cbranch_vccnz .LBB0_493
	s_cmp_lg_u32 s32, 0
	s_cbranch_scc1 .Lb_cont
	s_mov_b32 s32, 1
	v_or_b32_e32 v194, 0x400, v0
	v_or_b32_e32 v195, 0x800, v0
	v_or_b32_e32 v211, 0xc00, v0
	v_and_b32_e32 v254, 63, v0
	v_and_b32_e32 v2, 63, v0
	s_mov_b64 s[34:35], s[24:25]
	s_branch .Lconv_entry
.Lb_cont:
	s_ashr_i32 s21, s20, 1
	s_cmpk_gt_u32 s21, 0x7f
	v_readfirstlane_b32 s23, v0
	s_cbranch_scc1 .LBB0_486
	s_lshr_b32 s11, s23, 6
	s_or_b32 s34, s22, 12
	s_lshr_b32 s35, s21, 2
	s_lshr_b32 s10, s23, 8
	s_lshl_b32 s16, s11, 10
	s_lshl_b32 s12, s35, 20
	s_lshl_b32 s4, s34, 20
	s_add_u32 s8, s6, s4
	s_addc_u32 s9, s7, 0
	s_add_u32 s4, s8, 0x200000
	s_addc_u32 s5, s9, 0
	s_add_i32 s36, s16, 0
	v_lshl_or_b32 v134, v153, 12, v151
	s_add_i32 m0, s36, 0x10000
	v_lshl_or_b32 v130, v150, 12, v151
	global_load_lds_dwordx4 v134, s[4:5]
	s_add_i32 m0, s36, 0x12000
	s_add_u32 s8, s8, 0x280000
	global_load_lds_dwordx4 v130, s[4:5]
	s_addc_u32 s9, s9, 0
	s_add_i32 m0, s36, 0x14000
	v_lshl_or_b32 v136, v154, 12, v151
	global_load_lds_dwordx4 v134, s[8:9]
	s_add_i32 m0, s36, 0x16000
	s_add_u32 s13, s6, s12
	s_addc_u32 s15, s7, 0
	global_load_lds_dwordx4 v130, s[8:9]
	s_add_u32 s8, s13, 0x3000000
	s_addc_u32 s9, s15, 0
	s_add_i32 s37, s36, 0x2000
	s_mov_b32 m0, s36
	s_add_u32 s14, s13, 0x3080000
	v_lshl_or_b32 v132, v152, 12, v151
	global_load_lds_dwordx4 v136, s[8:9]
	s_mov_b32 m0, s37
	s_addc_u32 s15, s15, 0
	s_add_i32 s38, s36, 0x4000
	global_load_lds_dwordx4 v132, s[8:9]
	s_mov_b32 m0, s38
	s_add_i32 s39, s36, 0x6000
	global_load_lds_dwordx4 v136, s[14:15]
	s_mov_b32 m0, s39
	v_mov_b32_e32 v135, 0
	global_load_lds_dwordx4 v132, s[14:15]
	v_mov_b32_e32 v131, v135
	v_mov_b32_e32 v137, v135
	v_mov_b32_e32 v133, v135
	v_lshl_add_u64 v[8:9], s[4:5], 0, v[134:135]
	v_lshl_add_u64 v[6:7], s[4:5], 0, v[130:131]
	v_lshl_add_u64 v[4:5], s[8:9], 0, v[136:137]
	s_cmp_lg_u32 s10, 1
	v_lshl_add_u64 v[2:3], s[8:9], 0, v[132:133]
	s_cbranch_scc1 .LBB0_481
	s_barrier
